# misc routine moved onto the 40 workgroups that hold one GEMM tile fewer: 128-row passes, W staged through LDS in 256-deep chunks (double buffered), HX fragments from global
# speedup vs baseline: 1.0059x; 1.0059x over previous
.LBB0_359:
	s_mov_b64 exec, -1
	v_readlane_b32 s48, v253, 14
	s_mov_b32 s49, s33
	s_cmp_eq_u32 s33, 0x100
	s_cbranch_scc0 .Lmisc_any
	s_sub_u32 s48, s48, 64
	s_cmp_lt_u32 s48, 40
	s_cbranch_scc0 .Lmisc_done
	s_mov_b32 s49, 40
.Lmisc_any:
	s_cmpk_gt_u32 s48, 0x87
	s_cbranch_scc1 .Lmisc_done
	v_readfirstlane_b32 s4, v190
	s_lshr_b32 s4, s4, 6
	s_load_dwordx2 s[2:3], s[0:1], 0x100
	v_and_b32_e32 v0, 0x1ff, v190
	v_and_b32_e32 v10, 63, v0
	v_and_b32_e32 v11, 15, v10
	v_lshrrev_b32_e32 v3, 4, v10
	v_lshlrev_b32_e32 v3, 4, v3
	v_mul_u32_u24_e32 v2, 0x140, v11
	v_add_u32_e32 v2, v2, v3
	v_lshl_add_u32 v1, v11, 12, v3
	v_mul_u32_u24_e32 v8, 0x210, v11
	v_add_u32_e32 v8, v8, v3
	v_add_u32_e32 v9, 0xa500, v8
	v_lshrrev_b32_e32 v12, 5, v0
	v_and_b32_e32 v13, 31, v0
	v_lshlrev_b32_e32 v13, 4, v13
	v_lshl_add_u32 v5, v12, 12, v13
	v_mul_u32_u24_e32 v6, 0x210, v12
	v_add_u32_e32 v6, v6, v13
	v_add_u32_e32 v7, 0xa500, v6
	s_waitcnt lgkmcnt(0)
	s_add_u32 s18, s2, 0x1000000
	s_addc_u32 s19, s3, 0
	s_add_u32 s28, s2, 0x1010000
	s_addc_u32 s29, s3, 0
	s_add_u32 s30, s2, 0x1020000
	s_addc_u32 s31, s3, 0
	s_add_u32 s34, s2, 0x1030000
	s_addc_u32 s35, s3, 0
	s_add_u32 s36, s2, 0x1040000
	s_addc_u32 s37, s3, 0
	s_add_u32 s38, s2, 0x8884000
	s_addc_u32 s39, s3, 0
.Lmisc_pass:
	s_lshl_b32 s5, s48, 3
	s_add_i32 s5, s5, s4
	s_lshl_b32 s6, s5, 16
	s_lshr_b32 s7, s5, 16
	s_add_u32 s8, s2, s6
	s_addc_u32 s9, s3, s7
	s_add_u32 s8, s8, 0xe144d00
	s_addc_u32 s9, s9, 0
	s_mul_i32 s6, s5, 0x1400
	s_add_u32 s40, s2, s6
	s_addc_u32 s41, s3, 0
	s_add_u32 s40, s40, 0x21344d00
	s_addc_u32 s41, s41, 0
	v_mov_b64_e32 v[32:33], 0
	v_mov_b64_e32 v[34:35], 0
	v_mov_b64_e32 v[36:37], 0
	v_mov_b64_e32 v[38:39], 0
	v_mov_b64_e32 v[40:41], 0
	v_mov_b64_e32 v[42:43], 0
	v_mov_b64_e32 v[44:45], 0
	v_mov_b64_e32 v[46:47], 0
	v_mov_b64_e32 v[48:49], 0
	v_mov_b64_e32 v[50:51], 0
	global_load_dwordx4 v[136:139], v5, s[18:19]
	global_load_dwordx4 v[140:143], v5, s[28:29]
	global_load_dwordx4 v[144:147], v5, s[30:31]
	global_load_dwordx4 v[148:151], v5, s[34:35]
	global_load_dwordx4 v[152:155], v5, s[36:37]
	global_load_dwordx4 v[72:75], v1, s[8:9]
	global_load_dwordx4 v[76:79], v1, s[8:9] offset:64
	global_load_dwordx4 v[80:83], v1, s[8:9] offset:128
	global_load_dwordx4 v[84:87], v1, s[8:9] offset:192
	global_load_dwordx4 v[88:91], v1, s[8:9] offset:256
	global_load_dwordx4 v[92:95], v1, s[8:9] offset:320
	global_load_dwordx4 v[96:99], v1, s[8:9] offset:384
	global_load_dwordx4 v[100:103], v1, s[8:9] offset:448
	s_waitcnt vmcnt(8)
	ds_write_b128 v6, v[136:139]
	ds_write_b128 v6, v[140:143] offset:8448
	ds_write_b128 v6, v[144:147] offset:16896
	ds_write_b128 v6, v[148:151] offset:25344
	ds_write_b128 v6, v[152:155] offset:33792
	s_waitcnt lgkmcnt(0)
	s_barrier
	global_load_dwordx4 v[136:139], v5, s[18:19] offset:512
	global_load_dwordx4 v[140:143], v5, s[28:29] offset:512
	global_load_dwordx4 v[144:147], v5, s[30:31] offset:512
	global_load_dwordx4 v[148:151], v5, s[34:35] offset:512
	global_load_dwordx4 v[152:155], v5, s[36:37] offset:512
	global_load_dwordx4 v[104:107], v1, s[8:9] offset:512
	global_load_dwordx4 v[108:111], v1, s[8:9] offset:576
	global_load_dwordx4 v[112:115], v1, s[8:9] offset:640
	global_load_dwordx4 v[116:119], v1, s[8:9] offset:704
	global_load_dwordx4 v[120:123], v1, s[8:9] offset:768
	global_load_dwordx4 v[124:127], v1, s[8:9] offset:832
	global_load_dwordx4 v[128:131], v1, s[8:9] offset:896
	global_load_dwordx4 v[132:135], v1, s[8:9] offset:960
	s_waitcnt vmcnt(13)
	ds_read_b128 v[172:175], v8
	ds_read_b128 v[176:179], v8 offset:8448
	ds_read_b128 v[180:183], v8 offset:16896
	ds_read_b128 v[184:187], v8 offset:25344
	ds_read_b128 v[196:199], v8 offset:33792
	ds_read_b128 v[200:203], v8 offset:64
	ds_read_b128 v[204:207], v8 offset:8512
	ds_read_b128 v[208:211], v8 offset:16960
	ds_read_b128 v[212:215], v8 offset:25408
	ds_read_b128 v[234:237], v8 offset:33856
	s_waitcnt lgkmcnt(9)
	v_mfma_f32_16x16x32_bf16 v[32:35], v[172:175], v[72:75], v[32:35]
	ds_read_b128 v[172:175], v8 offset:128
	s_waitcnt lgkmcnt(9)
	v_mfma_f32_16x16x32_bf16 v[36:39], v[176:179], v[72:75], v[36:39]
	ds_read_b128 v[176:179], v8 offset:8576
	s_waitcnt lgkmcnt(9)
	v_mfma_f32_16x16x32_bf16 v[40:43], v[180:183], v[72:75], v[40:43]
	ds_read_b128 v[180:183], v8 offset:17024
	s_waitcnt lgkmcnt(9)
	v_mfma_f32_16x16x32_bf16 v[44:47], v[184:187], v[72:75], v[44:47]
	ds_read_b128 v[184:187], v8 offset:25472
	s_waitcnt lgkmcnt(9)
	v_mfma_f32_16x16x32_bf16 v[48:51], v[196:199], v[72:75], v[48:51]
	ds_read_b128 v[196:199], v8 offset:33920
	s_waitcnt lgkmcnt(9)
	v_mfma_f32_16x16x32_bf16 v[32:35], v[200:203], v[76:79], v[32:35]
	ds_read_b128 v[200:203], v8 offset:192
	s_waitcnt lgkmcnt(9)
	v_mfma_f32_16x16x32_bf16 v[36:39], v[204:207], v[76:79], v[36:39]
	ds_read_b128 v[204:207], v8 offset:8640
	s_waitcnt lgkmcnt(9)
	v_mfma_f32_16x16x32_bf16 v[40:43], v[208:211], v[76:79], v[40:43]
	ds_read_b128 v[208:211], v8 offset:17088
	s_waitcnt lgkmcnt(9)
	v_mfma_f32_16x16x32_bf16 v[44:47], v[212:215], v[76:79], v[44:47]
	ds_read_b128 v[212:215], v8 offset:25536
	s_waitcnt lgkmcnt(9)
	v_mfma_f32_16x16x32_bf16 v[48:51], v[234:237], v[76:79], v[48:51]
	ds_read_b128 v[234:237], v8 offset:33984
	s_waitcnt lgkmcnt(9)
	v_mfma_f32_16x16x32_bf16 v[32:35], v[172:175], v[80:83], v[32:35]
	ds_read_b128 v[172:175], v8 offset:256
	s_waitcnt lgkmcnt(9)
	v_mfma_f32_16x16x32_bf16 v[36:39], v[176:179], v[80:83], v[36:39]
	ds_read_b128 v[176:179], v8 offset:8704
	s_waitcnt lgkmcnt(9)
	v_mfma_f32_16x16x32_bf16 v[40:43], v[180:183], v[80:83], v[40:43]
	ds_read_b128 v[180:183], v8 offset:17152
	s_waitcnt lgkmcnt(9)
	v_mfma_f32_16x16x32_bf16 v[44:47], v[184:187], v[80:83], v[44:47]
	ds_read_b128 v[184:187], v8 offset:25600
	s_waitcnt lgkmcnt(9)
	v_mfma_f32_16x16x32_bf16 v[48:51], v[196:199], v[80:83], v[48:51]
	ds_read_b128 v[196:199], v8 offset:34048
	s_waitcnt lgkmcnt(9)
	v_mfma_f32_16x16x32_bf16 v[32:35], v[200:203], v[84:87], v[32:35]
	ds_read_b128 v[200:203], v8 offset:320
	s_waitcnt lgkmcnt(9)
	v_mfma_f32_16x16x32_bf16 v[36:39], v[204:207], v[84:87], v[36:39]
	ds_read_b128 v[204:207], v8 offset:8768
	s_waitcnt lgkmcnt(9)
	v_mfma_f32_16x16x32_bf16 v[40:43], v[208:211], v[84:87], v[40:43]
	ds_read_b128 v[208:211], v8 offset:17216
	s_waitcnt lgkmcnt(9)
	v_mfma_f32_16x16x32_bf16 v[44:47], v[212:215], v[84:87], v[44:47]
	ds_read_b128 v[212:215], v8 offset:25664
	s_waitcnt lgkmcnt(9)
	v_mfma_f32_16x16x32_bf16 v[48:51], v[234:237], v[84:87], v[48:51]
	ds_read_b128 v[234:237], v8 offset:34112
	s_waitcnt lgkmcnt(9)
	v_mfma_f32_16x16x32_bf16 v[32:35], v[172:175], v[88:91], v[32:35]
	ds_read_b128 v[172:175], v8 offset:384
	s_waitcnt lgkmcnt(9)
	v_mfma_f32_16x16x32_bf16 v[36:39], v[176:179], v[88:91], v[36:39]
	ds_read_b128 v[176:179], v8 offset:8832
	s_waitcnt lgkmcnt(9)
	v_mfma_f32_16x16x32_bf16 v[40:43], v[180:183], v[88:91], v[40:43]
	ds_read_b128 v[180:183], v8 offset:17280
	s_waitcnt lgkmcnt(9)
	v_mfma_f32_16x16x32_bf16 v[44:47], v[184:187], v[88:91], v[44:47]
	ds_read_b128 v[184:187], v8 offset:25728
	s_waitcnt lgkmcnt(9)
	v_mfma_f32_16x16x32_bf16 v[48:51], v[196:199], v[88:91], v[48:51]
	ds_read_b128 v[196:199], v8 offset:34176
	s_waitcnt lgkmcnt(9)
	v_mfma_f32_16x16x32_bf16 v[32:35], v[200:203], v[92:95], v[32:35]
	ds_read_b128 v[200:203], v8 offset:448
	s_waitcnt lgkmcnt(9)
	v_mfma_f32_16x16x32_bf16 v[36:39], v[204:207], v[92:95], v[36:39]
	ds_read_b128 v[204:207], v8 offset:8896
	s_waitcnt lgkmcnt(9)
	v_mfma_f32_16x16x32_bf16 v[40:43], v[208:211], v[92:95], v[40:43]
	ds_read_b128 v[208:211], v8 offset:17344
	s_waitcnt lgkmcnt(9)
	v_mfma_f32_16x16x32_bf16 v[44:47], v[212:215], v[92:95], v[44:47]
	ds_read_b128 v[212:215], v8 offset:25792
	s_waitcnt lgkmcnt(9)
	v_mfma_f32_16x16x32_bf16 v[48:51], v[234:237], v[92:95], v[48:51]
	ds_read_b128 v[234:237], v8 offset:34240
	s_waitcnt lgkmcnt(9)
	v_mfma_f32_16x16x32_bf16 v[32:35], v[172:175], v[96:99], v[32:35]
	s_waitcnt lgkmcnt(8)
	v_mfma_f32_16x16x32_bf16 v[36:39], v[176:179], v[96:99], v[36:39]
	s_waitcnt lgkmcnt(7)
	v_mfma_f32_16x16x32_bf16 v[40:43], v[180:183], v[96:99], v[40:43]
	s_waitcnt lgkmcnt(6)
	v_mfma_f32_16x16x32_bf16 v[44:47], v[184:187], v[96:99], v[44:47]
	s_waitcnt lgkmcnt(5)
	v_mfma_f32_16x16x32_bf16 v[48:51], v[196:199], v[96:99], v[48:51]
	s_waitcnt lgkmcnt(4)
	v_mfma_f32_16x16x32_bf16 v[32:35], v[200:203], v[100:103], v[32:35]
	s_waitcnt lgkmcnt(3)
	v_mfma_f32_16x16x32_bf16 v[36:39], v[204:207], v[100:103], v[36:39]
	s_waitcnt lgkmcnt(2)
	v_mfma_f32_16x16x32_bf16 v[40:43], v[208:211], v[100:103], v[40:43]
	s_waitcnt lgkmcnt(1)
	v_mfma_f32_16x16x32_bf16 v[44:47], v[212:215], v[100:103], v[44:47]
	s_waitcnt lgkmcnt(0)
	v_mfma_f32_16x16x32_bf16 v[48:51], v[234:237], v[100:103], v[48:51]
	s_waitcnt vmcnt(8)
	ds_write_b128 v7, v[136:139]
	ds_write_b128 v7, v[140:143] offset:8448
	ds_write_b128 v7, v[144:147] offset:16896
	ds_write_b128 v7, v[148:151] offset:25344
	ds_write_b128 v7, v[152:155] offset:33792
	s_waitcnt lgkmcnt(0)
	s_barrier
	global_load_dwordx4 v[136:139], v5, s[18:19] offset:1024
	global_load_dwordx4 v[140:143], v5, s[28:29] offset:1024
	global_load_dwordx4 v[144:147], v5, s[30:31] offset:1024
	global_load_dwordx4 v[148:151], v5, s[34:35] offset:1024
	global_load_dwordx4 v[152:155], v5, s[36:37] offset:1024
	global_load_dwordx4 v[72:75], v1, s[8:9] offset:1024
	global_load_dwordx4 v[76:79], v1, s[8:9] offset:1088
	global_load_dwordx4 v[80:83], v1, s[8:9] offset:1152
	global_load_dwordx4 v[84:87], v1, s[8:9] offset:1216
	global_load_dwordx4 v[88:91], v1, s[8:9] offset:1280
	global_load_dwordx4 v[92:95], v1, s[8:9] offset:1344
	global_load_dwordx4 v[96:99], v1, s[8:9] offset:1408
	global_load_dwordx4 v[100:103], v1, s[8:9] offset:1472
	s_waitcnt vmcnt(13)
	ds_read_b128 v[172:175], v9
	ds_read_b128 v[176:179], v9 offset:8448
	ds_read_b128 v[180:183], v9 offset:16896
	ds_read_b128 v[184:187], v9 offset:25344
	ds_read_b128 v[196:199], v9 offset:33792
	ds_read_b128 v[200:203], v9 offset:64
	ds_read_b128 v[204:207], v9 offset:8512
	ds_read_b128 v[208:211], v9 offset:16960
	ds_read_b128 v[212:215], v9 offset:25408
	ds_read_b128 v[234:237], v9 offset:33856
	s_waitcnt lgkmcnt(9)
	v_mfma_f32_16x16x32_bf16 v[32:35], v[172:175], v[104:107], v[32:35]
	ds_read_b128 v[172:175], v9 offset:128
	s_waitcnt lgkmcnt(9)
	v_mfma_f32_16x16x32_bf16 v[36:39], v[176:179], v[104:107], v[36:39]
	ds_read_b128 v[176:179], v9 offset:8576
	s_waitcnt lgkmcnt(9)
	v_mfma_f32_16x16x32_bf16 v[40:43], v[180:183], v[104:107], v[40:43]
	ds_read_b128 v[180:183], v9 offset:17024
	s_waitcnt lgkmcnt(9)
	v_mfma_f32_16x16x32_bf16 v[44:47], v[184:187], v[104:107], v[44:47]
	ds_read_b128 v[184:187], v9 offset:25472
	s_waitcnt lgkmcnt(9)
	v_mfma_f32_16x16x32_bf16 v[48:51], v[196:199], v[104:107], v[48:51]
	ds_read_b128 v[196:199], v9 offset:33920
	s_waitcnt lgkmcnt(9)
	v_mfma_f32_16x16x32_bf16 v[32:35], v[200:203], v[108:111], v[32:35]
	ds_read_b128 v[200:203], v9 offset:192
	s_waitcnt lgkmcnt(9)
	v_mfma_f32_16x16x32_bf16 v[36:39], v[204:207], v[108:111], v[36:39]
	ds_read_b128 v[204:207], v9 offset:8640
	s_waitcnt lgkmcnt(9)
	v_mfma_f32_16x16x32_bf16 v[40:43], v[208:211], v[108:111], v[40:43]
	ds_read_b128 v[208:211], v9 offset:17088
	s_waitcnt lgkmcnt(9)
	v_mfma_f32_16x16x32_bf16 v[44:47], v[212:215], v[108:111], v[44:47]
	ds_read_b128 v[212:215], v9 offset:25536
	s_waitcnt lgkmcnt(9)
	v_mfma_f32_16x16x32_bf16 v[48:51], v[234:237], v[108:111], v[48:51]
	ds_read_b128 v[234:237], v9 offset:33984
	s_waitcnt lgkmcnt(9)
	v_mfma_f32_16x16x32_bf16 v[32:35], v[172:175], v[112:115], v[32:35]
	ds_read_b128 v[172:175], v9 offset:256
	s_waitcnt lgkmcnt(9)
	v_mfma_f32_16x16x32_bf16 v[36:39], v[176:179], v[112:115], v[36:39]
	ds_read_b128 v[176:179], v9 offset:8704
	s_waitcnt lgkmcnt(9)
	v_mfma_f32_16x16x32_bf16 v[40:43], v[180:183], v[112:115], v[40:43]
	ds_read_b128 v[180:183], v9 offset:17152
	s_waitcnt lgkmcnt(9)
	v_mfma_f32_16x16x32_bf16 v[44:47], v[184:187], v[112:115], v[44:47]
	ds_read_b128 v[184:187], v9 offset:25600
	s_waitcnt lgkmcnt(9)
	v_mfma_f32_16x16x32_bf16 v[48:51], v[196:199], v[112:115], v[48:51]
	ds_read_b128 v[196:199], v9 offset:34048
	s_waitcnt lgkmcnt(9)
	v_mfma_f32_16x16x32_bf16 v[32:35], v[200:203], v[116:119], v[32:35]
	ds_read_b128 v[200:203], v9 offset:320
	s_waitcnt lgkmcnt(9)
	v_mfma_f32_16x16x32_bf16 v[36:39], v[204:207], v[116:119], v[36:39]
	ds_read_b128 v[204:207], v9 offset:8768
	s_waitcnt lgkmcnt(9)
	v_mfma_f32_16x16x32_bf16 v[40:43], v[208:211], v[116:119], v[40:43]
	ds_read_b128 v[208:211], v9 offset:17216
	s_waitcnt lgkmcnt(9)
	v_mfma_f32_16x16x32_bf16 v[44:47], v[212:215], v[116:119], v[44:47]
	ds_read_b128 v[212:215], v9 offset:25664
	s_waitcnt lgkmcnt(9)
	v_mfma_f32_16x16x32_bf16 v[48:51], v[234:237], v[116:119], v[48:51]
	ds_read_b128 v[234:237], v9 offset:34112
	s_waitcnt lgkmcnt(9)
	v_mfma_f32_16x16x32_bf16 v[32:35], v[172:175], v[120:123], v[32:35]
	ds_read_b128 v[172:175], v9 offset:384
	s_waitcnt lgkmcnt(9)
	v_mfma_f32_16x16x32_bf16 v[36:39], v[176:179], v[120:123], v[36:39]
	ds_read_b128 v[176:179], v9 offset:8832
	s_waitcnt lgkmcnt(9)
	v_mfma_f32_16x16x32_bf16 v[40:43], v[180:183], v[120:123], v[40:43]
	ds_read_b128 v[180:183], v9 offset:17280
	s_waitcnt lgkmcnt(9)
	v_mfma_f32_16x16x32_bf16 v[44:47], v[184:187], v[120:123], v[44:47]
	ds_read_b128 v[184:187], v9 offset:25728
	s_waitcnt lgkmcnt(9)
	v_mfma_f32_16x16x32_bf16 v[48:51], v[196:199], v[120:123], v[48:51]
	ds_read_b128 v[196:199], v9 offset:34176
	s_waitcnt lgkmcnt(9)
	v_mfma_f32_16x16x32_bf16 v[32:35], v[200:203], v[124:127], v[32:35]
	ds_read_b128 v[200:203], v9 offset:448
	s_waitcnt lgkmcnt(9)
	v_mfma_f32_16x16x32_bf16 v[36:39], v[204:207], v[124:127], v[36:39]
	ds_read_b128 v[204:207], v9 offset:8896
	s_waitcnt lgkmcnt(9)
	v_mfma_f32_16x16x32_bf16 v[40:43], v[208:211], v[124:127], v[40:43]
	ds_read_b128 v[208:211], v9 offset:17344
	s_waitcnt lgkmcnt(9)
	v_mfma_f32_16x16x32_bf16 v[44:47], v[212:215], v[124:127], v[44:47]
	ds_read_b128 v[212:215], v9 offset:25792
	s_waitcnt lgkmcnt(9)
	v_mfma_f32_16x16x32_bf16 v[48:51], v[234:237], v[124:127], v[48:51]
	ds_read_b128 v[234:237], v9 offset:34240
	s_waitcnt lgkmcnt(9)
	v_mfma_f32_16x16x32_bf16 v[32:35], v[172:175], v[128:131], v[32:35]
	s_waitcnt lgkmcnt(8)
	v_mfma_f32_16x16x32_bf16 v[36:39], v[176:179], v[128:131], v[36:39]
	s_waitcnt lgkmcnt(7)
	v_mfma_f32_16x16x32_bf16 v[40:43], v[180:183], v[128:131], v[40:43]
	s_waitcnt lgkmcnt(6)
	v_mfma_f32_16x16x32_bf16 v[44:47], v[184:187], v[128:131], v[44:47]
	s_waitcnt lgkmcnt(5)
	v_mfma_f32_16x16x32_bf16 v[48:51], v[196:199], v[128:131], v[48:51]
	s_waitcnt lgkmcnt(4)
	v_mfma_f32_16x16x32_bf16 v[32:35], v[200:203], v[132:135], v[32:35]
	s_waitcnt lgkmcnt(3)
	v_mfma_f32_16x16x32_bf16 v[36:39], v[204:207], v[132:135], v[36:39]
	s_waitcnt lgkmcnt(2)
	v_mfma_f32_16x16x32_bf16 v[40:43], v[208:211], v[132:135], v[40:43]
	s_waitcnt lgkmcnt(1)
	v_mfma_f32_16x16x32_bf16 v[44:47], v[212:215], v[132:135], v[44:47]
	s_waitcnt lgkmcnt(0)
	v_mfma_f32_16x16x32_bf16 v[48:51], v[234:237], v[132:135], v[48:51]
	s_waitcnt vmcnt(8)
	ds_write_b128 v6, v[136:139]
	ds_write_b128 v6, v[140:143] offset:8448
	ds_write_b128 v6, v[144:147] offset:16896
	ds_write_b128 v6, v[148:151] offset:25344
	ds_write_b128 v6, v[152:155] offset:33792
	s_waitcnt lgkmcnt(0)
	s_barrier
	global_load_dwordx4 v[136:139], v5, s[18:19] offset:1536
	global_load_dwordx4 v[140:143], v5, s[28:29] offset:1536
	global_load_dwordx4 v[144:147], v5, s[30:31] offset:1536
	global_load_dwordx4 v[148:151], v5, s[34:35] offset:1536
	global_load_dwordx4 v[152:155], v5, s[36:37] offset:1536
	global_load_dwordx4 v[104:107], v1, s[8:9] offset:1536
	global_load_dwordx4 v[108:111], v1, s[8:9] offset:1600
	global_load_dwordx4 v[112:115], v1, s[8:9] offset:1664
	global_load_dwordx4 v[116:119], v1, s[8:9] offset:1728
	global_load_dwordx4 v[120:123], v1, s[8:9] offset:1792
	global_load_dwordx4 v[124:127], v1, s[8:9] offset:1856
	global_load_dwordx4 v[128:131], v1, s[8:9] offset:1920
	global_load_dwordx4 v[132:135], v1, s[8:9] offset:1984
	s_waitcnt vmcnt(13)
	ds_read_b128 v[172:175], v8
	ds_read_b128 v[176:179], v8 offset:8448
	ds_read_b128 v[180:183], v8 offset:16896
	ds_read_b128 v[184:187], v8 offset:25344
	ds_read_b128 v[196:199], v8 offset:33792
	ds_read_b128 v[200:203], v8 offset:64
	ds_read_b128 v[204:207], v8 offset:8512
	ds_read_b128 v[208:211], v8 offset:16960
	ds_read_b128 v[212:215], v8 offset:25408
	ds_read_b128 v[234:237], v8 offset:33856
	s_waitcnt lgkmcnt(9)
	v_mfma_f32_16x16x32_bf16 v[32:35], v[172:175], v[72:75], v[32:35]
	ds_read_b128 v[172:175], v8 offset:128
	s_waitcnt lgkmcnt(9)
	v_mfma_f32_16x16x32_bf16 v[36:39], v[176:179], v[72:75], v[36:39]
	ds_read_b128 v[176:179], v8 offset:8576
	s_waitcnt lgkmcnt(9)
	v_mfma_f32_16x16x32_bf16 v[40:43], v[180:183], v[72:75], v[40:43]
	ds_read_b128 v[180:183], v8 offset:17024
	s_waitcnt lgkmcnt(9)
	v_mfma_f32_16x16x32_bf16 v[44:47], v[184:187], v[72:75], v[44:47]
	ds_read_b128 v[184:187], v8 offset:25472
	s_waitcnt lgkmcnt(9)
	v_mfma_f32_16x16x32_bf16 v[48:51], v[196:199], v[72:75], v[48:51]
	ds_read_b128 v[196:199], v8 offset:33920
	s_waitcnt lgkmcnt(9)
	v_mfma_f32_16x16x32_bf16 v[32:35], v[200:203], v[76:79], v[32:35]
	ds_read_b128 v[200:203], v8 offset:192
	s_waitcnt lgkmcnt(9)
	v_mfma_f32_16x16x32_bf16 v[36:39], v[204:207], v[76:79], v[36:39]
	ds_read_b128 v[204:207], v8 offset:8640
	s_waitcnt lgkmcnt(9)
	v_mfma_f32_16x16x32_bf16 v[40:43], v[208:211], v[76:79], v[40:43]
	ds_read_b128 v[208:211], v8 offset:17088
	s_waitcnt lgkmcnt(9)
	v_mfma_f32_16x16x32_bf16 v[44:47], v[212:215], v[76:79], v[44:47]
	ds_read_b128 v[212:215], v8 offset:25536
	s_waitcnt lgkmcnt(9)
	v_mfma_f32_16x16x32_bf16 v[48:51], v[234:237], v[76:79], v[48:51]
	ds_read_b128 v[234:237], v8 offset:33984
	s_waitcnt lgkmcnt(9)
	v_mfma_f32_16x16x32_bf16 v[32:35], v[172:175], v[80:83], v[32:35]
	ds_read_b128 v[172:175], v8 offset:256
	s_waitcnt lgkmcnt(9)
	v_mfma_f32_16x16x32_bf16 v[36:39], v[176:179], v[80:83], v[36:39]
	ds_read_b128 v[176:179], v8 offset:8704
	s_waitcnt lgkmcnt(9)
	v_mfma_f32_16x16x32_bf16 v[40:43], v[180:183], v[80:83], v[40:43]
	ds_read_b128 v[180:183], v8 offset:17152
	s_waitcnt lgkmcnt(9)
	v_mfma_f32_16x16x32_bf16 v[44:47], v[184:187], v[80:83], v[44:47]
	ds_read_b128 v[184:187], v8 offset:25600
	s_waitcnt lgkmcnt(9)
	v_mfma_f32_16x16x32_bf16 v[48:51], v[196:199], v[80:83], v[48:51]
	ds_read_b128 v[196:199], v8 offset:34048
	s_waitcnt lgkmcnt(9)
	v_mfma_f32_16x16x32_bf16 v[32:35], v[200:203], v[84:87], v[32:35]
	ds_read_b128 v[200:203], v8 offset:320
	s_waitcnt lgkmcnt(9)
	v_mfma_f32_16x16x32_bf16 v[36:39], v[204:207], v[84:87], v[36:39]
	ds_read_b128 v[204:207], v8 offset:8768
	s_waitcnt lgkmcnt(9)
	v_mfma_f32_16x16x32_bf16 v[40:43], v[208:211], v[84:87], v[40:43]
	ds_read_b128 v[208:211], v8 offset:17216
	s_waitcnt lgkmcnt(9)
	v_mfma_f32_16x16x32_bf16 v[44:47], v[212:215], v[84:87], v[44:47]
	ds_read_b128 v[212:215], v8 offset:25664
	s_waitcnt lgkmcnt(9)
	v_mfma_f32_16x16x32_bf16 v[48:51], v[234:237], v[84:87], v[48:51]
	ds_read_b128 v[234:237], v8 offset:34112
	s_waitcnt lgkmcnt(9)
	v_mfma_f32_16x16x32_bf16 v[32:35], v[172:175], v[88:91], v[32:35]
	ds_read_b128 v[172:175], v8 offset:384
	s_waitcnt lgkmcnt(9)
	v_mfma_f32_16x16x32_bf16 v[36:39], v[176:179], v[88:91], v[36:39]
	ds_read_b128 v[176:179], v8 offset:8832
	s_waitcnt lgkmcnt(9)
	v_mfma_f32_16x16x32_bf16 v[40:43], v[180:183], v[88:91], v[40:43]
	ds_read_b128 v[180:183], v8 offset:17280
	s_waitcnt lgkmcnt(9)
	v_mfma_f32_16x16x32_bf16 v[44:47], v[184:187], v[88:91], v[44:47]
	ds_read_b128 v[184:187], v8 offset:25728
	s_waitcnt lgkmcnt(9)
	v_mfma_f32_16x16x32_bf16 v[48:51], v[196:199], v[88:91], v[48:51]
	ds_read_b128 v[196:199], v8 offset:34176
	s_waitcnt lgkmcnt(9)
	v_mfma_f32_16x16x32_bf16 v[32:35], v[200:203], v[92:95], v[32:35]
	ds_read_b128 v[200:203], v8 offset:448
	s_waitcnt lgkmcnt(9)
	v_mfma_f32_16x16x32_bf16 v[36:39], v[204:207], v[92:95], v[36:39]
	ds_read_b128 v[204:207], v8 offset:8896
	s_waitcnt lgkmcnt(9)
	v_mfma_f32_16x16x32_bf16 v[40:43], v[208:211], v[92:95], v[40:43]
	ds_read_b128 v[208:211], v8 offset:17344
	s_waitcnt lgkmcnt(9)
	v_mfma_f32_16x16x32_bf16 v[44:47], v[212:215], v[92:95], v[44:47]
	ds_read_b128 v[212:215], v8 offset:25792
	s_waitcnt lgkmcnt(9)
	v_mfma_f32_16x16x32_bf16 v[48:51], v[234:237], v[92:95], v[48:51]
	ds_read_b128 v[234:237], v8 offset:34240
	s_waitcnt lgkmcnt(9)
	v_mfma_f32_16x16x32_bf16 v[32:35], v[172:175], v[96:99], v[32:35]
	s_waitcnt lgkmcnt(8)
	v_mfma_f32_16x16x32_bf16 v[36:39], v[176:179], v[96:99], v[36:39]
	s_waitcnt lgkmcnt(7)
	v_mfma_f32_16x16x32_bf16 v[40:43], v[180:183], v[96:99], v[40:43]
	s_waitcnt lgkmcnt(6)
	v_mfma_f32_16x16x32_bf16 v[44:47], v[184:187], v[96:99], v[44:47]
	s_waitcnt lgkmcnt(5)
	v_mfma_f32_16x16x32_bf16 v[48:51], v[196:199], v[96:99], v[48:51]
	s_waitcnt lgkmcnt(4)
	v_mfma_f32_16x16x32_bf16 v[32:35], v[200:203], v[100:103], v[32:35]
	s_waitcnt lgkmcnt(3)
	v_mfma_f32_16x16x32_bf16 v[36:39], v[204:207], v[100:103], v[36:39]
	s_waitcnt lgkmcnt(2)
	v_mfma_f32_16x16x32_bf16 v[40:43], v[208:211], v[100:103], v[40:43]
	s_waitcnt lgkmcnt(1)
	v_mfma_f32_16x16x32_bf16 v[44:47], v[212:215], v[100:103], v[44:47]
	s_waitcnt lgkmcnt(0)
	v_mfma_f32_16x16x32_bf16 v[48:51], v[234:237], v[100:103], v[48:51]
	s_waitcnt vmcnt(8)
	ds_write_b128 v7, v[136:139]
	ds_write_b128 v7, v[140:143] offset:8448
	ds_write_b128 v7, v[144:147] offset:16896
	ds_write_b128 v7, v[148:151] offset:25344
	ds_write_b128 v7, v[152:155] offset:33792
	s_waitcnt lgkmcnt(0)
	s_barrier
	global_load_dwordx4 v[136:139], v5, s[18:19] offset:2048
	global_load_dwordx4 v[140:143], v5, s[28:29] offset:2048
	global_load_dwordx4 v[144:147], v5, s[30:31] offset:2048
	global_load_dwordx4 v[148:151], v5, s[34:35] offset:2048
	global_load_dwordx4 v[152:155], v5, s[36:37] offset:2048
	global_load_dwordx4 v[72:75], v1, s[8:9] offset:2048
	global_load_dwordx4 v[76:79], v1, s[8:9] offset:2112
	global_load_dwordx4 v[80:83], v1, s[8:9] offset:2176
	global_load_dwordx4 v[84:87], v1, s[8:9] offset:2240
	global_load_dwordx4 v[88:91], v1, s[8:9] offset:2304
	global_load_dwordx4 v[92:95], v1, s[8:9] offset:2368
	global_load_dwordx4 v[96:99], v1, s[8:9] offset:2432
	global_load_dwordx4 v[100:103], v1, s[8:9] offset:2496
	s_waitcnt vmcnt(13)
	ds_read_b128 v[172:175], v9
	ds_read_b128 v[176:179], v9 offset:8448
	ds_read_b128 v[180:183], v9 offset:16896
	ds_read_b128 v[184:187], v9 offset:25344
	ds_read_b128 v[196:199], v9 offset:33792
	ds_read_b128 v[200:203], v9 offset:64
	ds_read_b128 v[204:207], v9 offset:8512
	ds_read_b128 v[208:211], v9 offset:16960
	ds_read_b128 v[212:215], v9 offset:25408
	ds_read_b128 v[234:237], v9 offset:33856
	s_waitcnt lgkmcnt(9)
	v_mfma_f32_16x16x32_bf16 v[32:35], v[172:175], v[104:107], v[32:35]
	ds_read_b128 v[172:175], v9 offset:128
	s_waitcnt lgkmcnt(9)
	v_mfma_f32_16x16x32_bf16 v[36:39], v[176:179], v[104:107], v[36:39]
	ds_read_b128 v[176:179], v9 offset:8576
	s_waitcnt lgkmcnt(9)
	v_mfma_f32_16x16x32_bf16 v[40:43], v[180:183], v[104:107], v[40:43]
	ds_read_b128 v[180:183], v9 offset:17024
	s_waitcnt lgkmcnt(9)
	v_mfma_f32_16x16x32_bf16 v[44:47], v[184:187], v[104:107], v[44:47]
	ds_read_b128 v[184:187], v9 offset:25472
	s_waitcnt lgkmcnt(9)
	v_mfma_f32_16x16x32_bf16 v[48:51], v[196:199], v[104:107], v[48:51]
	ds_read_b128 v[196:199], v9 offset:33920
	s_waitcnt lgkmcnt(9)
	v_mfma_f32_16x16x32_bf16 v[32:35], v[200:203], v[108:111], v[32:35]
	ds_read_b128 v[200:203], v9 offset:192
	s_waitcnt lgkmcnt(9)
	v_mfma_f32_16x16x32_bf16 v[36:39], v[204:207], v[108:111], v[36:39]
	ds_read_b128 v[204:207], v9 offset:8640
	s_waitcnt lgkmcnt(9)
	v_mfma_f32_16x16x32_bf16 v[40:43], v[208:211], v[108:111], v[40:43]
	ds_read_b128 v[208:211], v9 offset:17088
	s_waitcnt lgkmcnt(9)
	v_mfma_f32_16x16x32_bf16 v[44:47], v[212:215], v[108:111], v[44:47]
	ds_read_b128 v[212:215], v9 offset:25536
	s_waitcnt lgkmcnt(9)
	v_mfma_f32_16x16x32_bf16 v[48:51], v[234:237], v[108:111], v[48:51]
	ds_read_b128 v[234:237], v9 offset:33984
	s_waitcnt lgkmcnt(9)
	v_mfma_f32_16x16x32_bf16 v[32:35], v[172:175], v[112:115], v[32:35]
	ds_read_b128 v[172:175], v9 offset:256
	s_waitcnt lgkmcnt(9)
	v_mfma_f32_16x16x32_bf16 v[36:39], v[176:179], v[112:115], v[36:39]
	ds_read_b128 v[176:179], v9 offset:8704
	s_waitcnt lgkmcnt(9)
	v_mfma_f32_16x16x32_bf16 v[40:43], v[180:183], v[112:115], v[40:43]
	ds_read_b128 v[180:183], v9 offset:17152
	s_waitcnt lgkmcnt(9)
	v_mfma_f32_16x16x32_bf16 v[44:47], v[184:187], v[112:115], v[44:47]
	ds_read_b128 v[184:187], v9 offset:25600
	s_waitcnt lgkmcnt(9)
	v_mfma_f32_16x16x32_bf16 v[48:51], v[196:199], v[112:115], v[48:51]
	ds_read_b128 v[196:199], v9 offset:34048
	s_waitcnt lgkmcnt(9)
	v_mfma_f32_16x16x32_bf16 v[32:35], v[200:203], v[116:119], v[32:35]
	ds_read_b128 v[200:203], v9 offset:320
	s_waitcnt lgkmcnt(9)
	v_mfma_f32_16x16x32_bf16 v[36:39], v[204:207], v[116:119], v[36:39]
	ds_read_b128 v[204:207], v9 offset:8768
	s_waitcnt lgkmcnt(9)
	v_mfma_f32_16x16x32_bf16 v[40:43], v[208:211], v[116:119], v[40:43]
	ds_read_b128 v[208:211], v9 offset:17216
	s_waitcnt lgkmcnt(9)
	v_mfma_f32_16x16x32_bf16 v[44:47], v[212:215], v[116:119], v[44:47]
	ds_read_b128 v[212:215], v9 offset:25664
	s_waitcnt lgkmcnt(9)
	v_mfma_f32_16x16x32_bf16 v[48:51], v[234:237], v[116:119], v[48:51]
	ds_read_b128 v[234:237], v9 offset:34112
	s_waitcnt lgkmcnt(9)
	v_mfma_f32_16x16x32_bf16 v[32:35], v[172:175], v[120:123], v[32:35]
	ds_read_b128 v[172:175], v9 offset:384
	s_waitcnt lgkmcnt(9)
	v_mfma_f32_16x16x32_bf16 v[36:39], v[176:179], v[120:123], v[36:39]
	ds_read_b128 v[176:179], v9 offset:8832
	s_waitcnt lgkmcnt(9)
	v_mfma_f32_16x16x32_bf16 v[40:43], v[180:183], v[120:123], v[40:43]
	ds_read_b128 v[180:183], v9 offset:17280
	s_waitcnt lgkmcnt(9)
	v_mfma_f32_16x16x32_bf16 v[44:47], v[184:187], v[120:123], v[44:47]
	ds_read_b128 v[184:187], v9 offset:25728
	s_waitcnt lgkmcnt(9)
	v_mfma_f32_16x16x32_bf16 v[48:51], v[196:199], v[120:123], v[48:51]
	ds_read_b128 v[196:199], v9 offset:34176
	s_waitcnt lgkmcnt(9)
	v_mfma_f32_16x16x32_bf16 v[32:35], v[200:203], v[124:127], v[32:35]
	ds_read_b128 v[200:203], v9 offset:448
	s_waitcnt lgkmcnt(9)
	v_mfma_f32_16x16x32_bf16 v[36:39], v[204:207], v[124:127], v[36:39]
	ds_read_b128 v[204:207], v9 offset:8896
	s_waitcnt lgkmcnt(9)
	v_mfma_f32_16x16x32_bf16 v[40:43], v[208:211], v[124:127], v[40:43]
	ds_read_b128 v[208:211], v9 offset:17344
	s_waitcnt lgkmcnt(9)
	v_mfma_f32_16x16x32_bf16 v[44:47], v[212:215], v[124:127], v[44:47]
	ds_read_b128 v[212:215], v9 offset:25792
	s_waitcnt lgkmcnt(9)
	v_mfma_f32_16x16x32_bf16 v[48:51], v[234:237], v[124:127], v[48:51]
	ds_read_b128 v[234:237], v9 offset:34240
	s_waitcnt lgkmcnt(9)
	v_mfma_f32_16x16x32_bf16 v[32:35], v[172:175], v[128:131], v[32:35]
	s_waitcnt lgkmcnt(8)
	v_mfma_f32_16x16x32_bf16 v[36:39], v[176:179], v[128:131], v[36:39]
	s_waitcnt lgkmcnt(7)
	v_mfma_f32_16x16x32_bf16 v[40:43], v[180:183], v[128:131], v[40:43]
	s_waitcnt lgkmcnt(6)
	v_mfma_f32_16x16x32_bf16 v[44:47], v[184:187], v[128:131], v[44:47]
	s_waitcnt lgkmcnt(5)
	v_mfma_f32_16x16x32_bf16 v[48:51], v[196:199], v[128:131], v[48:51]
	s_waitcnt lgkmcnt(4)
	v_mfma_f32_16x16x32_bf16 v[32:35], v[200:203], v[132:135], v[32:35]
	s_waitcnt lgkmcnt(3)
	v_mfma_f32_16x16x32_bf16 v[36:39], v[204:207], v[132:135], v[36:39]
	s_waitcnt lgkmcnt(2)
	v_mfma_f32_16x16x32_bf16 v[40:43], v[208:211], v[132:135], v[40:43]
	s_waitcnt lgkmcnt(1)
	v_mfma_f32_16x16x32_bf16 v[44:47], v[212:215], v[132:135], v[44:47]
	s_waitcnt lgkmcnt(0)
	v_mfma_f32_16x16x32_bf16 v[48:51], v[234:237], v[132:135], v[48:51]
	s_waitcnt vmcnt(8)
	ds_write_b128 v6, v[136:139]
	ds_write_b128 v6, v[140:143] offset:8448
	ds_write_b128 v6, v[144:147] offset:16896
	ds_write_b128 v6, v[148:151] offset:25344
	ds_write_b128 v6, v[152:155] offset:33792
	s_waitcnt lgkmcnt(0)
	s_barrier
	global_load_dwordx4 v[136:139], v5, s[18:19] offset:2560
	global_load_dwordx4 v[140:143], v5, s[28:29] offset:2560
	global_load_dwordx4 v[144:147], v5, s[30:31] offset:2560
	global_load_dwordx4 v[148:151], v5, s[34:35] offset:2560
	global_load_dwordx4 v[152:155], v5, s[36:37] offset:2560
	global_load_dwordx4 v[104:107], v1, s[8:9] offset:2560
	global_load_dwordx4 v[108:111], v1, s[8:9] offset:2624
	global_load_dwordx4 v[112:115], v1, s[8:9] offset:2688
	global_load_dwordx4 v[116:119], v1, s[8:9] offset:2752
	global_load_dwordx4 v[120:123], v1, s[8:9] offset:2816
	global_load_dwordx4 v[124:127], v1, s[8:9] offset:2880
	global_load_dwordx4 v[128:131], v1, s[8:9] offset:2944
	global_load_dwordx4 v[132:135], v1, s[8:9] offset:3008
	s_waitcnt vmcnt(13)
	ds_read_b128 v[172:175], v8
	ds_read_b128 v[176:179], v8 offset:8448
	ds_read_b128 v[180:183], v8 offset:16896
	ds_read_b128 v[184:187], v8 offset:25344
	ds_read_b128 v[196:199], v8 offset:33792
	ds_read_b128 v[200:203], v8 offset:64
	ds_read_b128 v[204:207], v8 offset:8512
	ds_read_b128 v[208:211], v8 offset:16960
	ds_read_b128 v[212:215], v8 offset:25408
	ds_read_b128 v[234:237], v8 offset:33856
	s_waitcnt lgkmcnt(9)
	v_mfma_f32_16x16x32_bf16 v[32:35], v[172:175], v[72:75], v[32:35]
	ds_read_b128 v[172:175], v8 offset:128
	s_waitcnt lgkmcnt(9)
	v_mfma_f32_16x16x32_bf16 v[36:39], v[176:179], v[72:75], v[36:39]
	ds_read_b128 v[176:179], v8 offset:8576
	s_waitcnt lgkmcnt(9)
	v_mfma_f32_16x16x32_bf16 v[40:43], v[180:183], v[72:75], v[40:43]
	ds_read_b128 v[180:183], v8 offset:17024
	s_waitcnt lgkmcnt(9)
	v_mfma_f32_16x16x32_bf16 v[44:47], v[184:187], v[72:75], v[44:47]
	ds_read_b128 v[184:187], v8 offset:25472
	s_waitcnt lgkmcnt(9)
	v_mfma_f32_16x16x32_bf16 v[48:51], v[196:199], v[72:75], v[48:51]
	ds_read_b128 v[196:199], v8 offset:33920
	s_waitcnt lgkmcnt(9)
	v_mfma_f32_16x16x32_bf16 v[32:35], v[200:203], v[76:79], v[32:35]
	ds_read_b128 v[200:203], v8 offset:192
	s_waitcnt lgkmcnt(9)
	v_mfma_f32_16x16x32_bf16 v[36:39], v[204:207], v[76:79], v[36:39]
	ds_read_b128 v[204:207], v8 offset:8640
	s_waitcnt lgkmcnt(9)
	v_mfma_f32_16x16x32_bf16 v[40:43], v[208:211], v[76:79], v[40:43]
	ds_read_b128 v[208:211], v8 offset:17088
	s_waitcnt lgkmcnt(9)
	v_mfma_f32_16x16x32_bf16 v[44:47], v[212:215], v[76:79], v[44:47]
	ds_read_b128 v[212:215], v8 offset:25536
	s_waitcnt lgkmcnt(9)
	v_mfma_f32_16x16x32_bf16 v[48:51], v[234:237], v[76:79], v[48:51]
	ds_read_b128 v[234:237], v8 offset:33984
	s_waitcnt lgkmcnt(9)
	v_mfma_f32_16x16x32_bf16 v[32:35], v[172:175], v[80:83], v[32:35]
	ds_read_b128 v[172:175], v8 offset:256
	s_waitcnt lgkmcnt(9)
	v_mfma_f32_16x16x32_bf16 v[36:39], v[176:179], v[80:83], v[36:39]
	ds_read_b128 v[176:179], v8 offset:8704
	s_waitcnt lgkmcnt(9)
	v_mfma_f32_16x16x32_bf16 v[40:43], v[180:183], v[80:83], v[40:43]
	ds_read_b128 v[180:183], v8 offset:17152
	s_waitcnt lgkmcnt(9)
	v_mfma_f32_16x16x32_bf16 v[44:47], v[184:187], v[80:83], v[44:47]
	ds_read_b128 v[184:187], v8 offset:25600
	s_waitcnt lgkmcnt(9)
	v_mfma_f32_16x16x32_bf16 v[48:51], v[196:199], v[80:83], v[48:51]
	ds_read_b128 v[196:199], v8 offset:34048
	s_waitcnt lgkmcnt(9)
	v_mfma_f32_16x16x32_bf16 v[32:35], v[200:203], v[84:87], v[32:35]
	ds_read_b128 v[200:203], v8 offset:320
	s_waitcnt lgkmcnt(9)
	v_mfma_f32_16x16x32_bf16 v[36:39], v[204:207], v[84:87], v[36:39]
	ds_read_b128 v[204:207], v8 offset:8768
	s_waitcnt lgkmcnt(9)
	v_mfma_f32_16x16x32_bf16 v[40:43], v[208:211], v[84:87], v[40:43]
	ds_read_b128 v[208:211], v8 offset:17216
	s_waitcnt lgkmcnt(9)
	v_mfma_f32_16x16x32_bf16 v[44:47], v[212:215], v[84:87], v[44:47]
	ds_read_b128 v[212:215], v8 offset:25664
	s_waitcnt lgkmcnt(9)
	v_mfma_f32_16x16x32_bf16 v[48:51], v[234:237], v[84:87], v[48:51]
	ds_read_b128 v[234:237], v8 offset:34112
	s_waitcnt lgkmcnt(9)
	v_mfma_f32_16x16x32_bf16 v[32:35], v[172:175], v[88:91], v[32:35]
	ds_read_b128 v[172:175], v8 offset:384
	s_waitcnt lgkmcnt(9)
	v_mfma_f32_16x16x32_bf16 v[36:39], v[176:179], v[88:91], v[36:39]
	ds_read_b128 v[176:179], v8 offset:8832
	s_waitcnt lgkmcnt(9)
	v_mfma_f32_16x16x32_bf16 v[40:43], v[180:183], v[88:91], v[40:43]
	ds_read_b128 v[180:183], v8 offset:17280
	s_waitcnt lgkmcnt(9)
	v_mfma_f32_16x16x32_bf16 v[44:47], v[184:187], v[88:91], v[44:47]
	ds_read_b128 v[184:187], v8 offset:25728
	s_waitcnt lgkmcnt(9)
	v_mfma_f32_16x16x32_bf16 v[48:51], v[196:199], v[88:91], v[48:51]
	ds_read_b128 v[196:199], v8 offset:34176
	s_waitcnt lgkmcnt(9)
	v_mfma_f32_16x16x32_bf16 v[32:35], v[200:203], v[92:95], v[32:35]
	ds_read_b128 v[200:203], v8 offset:448
	s_waitcnt lgkmcnt(9)
	v_mfma_f32_16x16x32_bf16 v[36:39], v[204:207], v[92:95], v[36:39]
	ds_read_b128 v[204:207], v8 offset:8896
	s_waitcnt lgkmcnt(9)
	v_mfma_f32_16x16x32_bf16 v[40:43], v[208:211], v[92:95], v[40:43]
	ds_read_b128 v[208:211], v8 offset:17344
	s_waitcnt lgkmcnt(9)
	v_mfma_f32_16x16x32_bf16 v[44:47], v[212:215], v[92:95], v[44:47]
	ds_read_b128 v[212:215], v8 offset:25792
	s_waitcnt lgkmcnt(9)
	v_mfma_f32_16x16x32_bf16 v[48:51], v[234:237], v[92:95], v[48:51]
	ds_read_b128 v[234:237], v8 offset:34240
	s_waitcnt lgkmcnt(9)
	v_mfma_f32_16x16x32_bf16 v[32:35], v[172:175], v[96:99], v[32:35]
	s_waitcnt lgkmcnt(8)
	v_mfma_f32_16x16x32_bf16 v[36:39], v[176:179], v[96:99], v[36:39]
	s_waitcnt lgkmcnt(7)
	v_mfma_f32_16x16x32_bf16 v[40:43], v[180:183], v[96:99], v[40:43]
	s_waitcnt lgkmcnt(6)
	v_mfma_f32_16x16x32_bf16 v[44:47], v[184:187], v[96:99], v[44:47]
	s_waitcnt lgkmcnt(5)
	v_mfma_f32_16x16x32_bf16 v[48:51], v[196:199], v[96:99], v[48:51]
	s_waitcnt lgkmcnt(4)
	v_mfma_f32_16x16x32_bf16 v[32:35], v[200:203], v[100:103], v[32:35]
	s_waitcnt lgkmcnt(3)
	v_mfma_f32_16x16x32_bf16 v[36:39], v[204:207], v[100:103], v[36:39]
	s_waitcnt lgkmcnt(2)
	v_mfma_f32_16x16x32_bf16 v[40:43], v[208:211], v[100:103], v[40:43]
	s_waitcnt lgkmcnt(1)
	v_mfma_f32_16x16x32_bf16 v[44:47], v[212:215], v[100:103], v[44:47]
	s_waitcnt lgkmcnt(0)
	v_mfma_f32_16x16x32_bf16 v[48:51], v[234:237], v[100:103], v[48:51]
	s_waitcnt vmcnt(8)
	ds_write_b128 v7, v[136:139]
	ds_write_b128 v7, v[140:143] offset:8448
	ds_write_b128 v7, v[144:147] offset:16896
	ds_write_b128 v7, v[148:151] offset:25344
	ds_write_b128 v7, v[152:155] offset:33792
	s_waitcnt lgkmcnt(0)
	s_barrier
	global_load_dwordx4 v[136:139], v5, s[18:19] offset:3072
	global_load_dwordx4 v[140:143], v5, s[28:29] offset:3072
	global_load_dwordx4 v[144:147], v5, s[30:31] offset:3072
	global_load_dwordx4 v[148:151], v5, s[34:35] offset:3072
	global_load_dwordx4 v[152:155], v5, s[36:37] offset:3072
	global_load_dwordx4 v[72:75], v1, s[8:9] offset:3072
	global_load_dwordx4 v[76:79], v1, s[8:9] offset:3136
	global_load_dwordx4 v[80:83], v1, s[8:9] offset:3200
	global_load_dwordx4 v[84:87], v1, s[8:9] offset:3264
	global_load_dwordx4 v[88:91], v1, s[8:9] offset:3328
	global_load_dwordx4 v[92:95], v1, s[8:9] offset:3392
	global_load_dwordx4 v[96:99], v1, s[8:9] offset:3456
	global_load_dwordx4 v[100:103], v1, s[8:9] offset:3520
	s_waitcnt vmcnt(13)
	ds_read_b128 v[172:175], v9
	ds_read_b128 v[176:179], v9 offset:8448
	ds_read_b128 v[180:183], v9 offset:16896
	ds_read_b128 v[184:187], v9 offset:25344
	ds_read_b128 v[196:199], v9 offset:33792
	ds_read_b128 v[200:203], v9 offset:64
	ds_read_b128 v[204:207], v9 offset:8512
	ds_read_b128 v[208:211], v9 offset:16960
	ds_read_b128 v[212:215], v9 offset:25408
	ds_read_b128 v[234:237], v9 offset:33856
	s_waitcnt lgkmcnt(9)
	v_mfma_f32_16x16x32_bf16 v[32:35], v[172:175], v[104:107], v[32:35]
	ds_read_b128 v[172:175], v9 offset:128
	s_waitcnt lgkmcnt(9)
	v_mfma_f32_16x16x32_bf16 v[36:39], v[176:179], v[104:107], v[36:39]
	ds_read_b128 v[176:179], v9 offset:8576
	s_waitcnt lgkmcnt(9)
	v_mfma_f32_16x16x32_bf16 v[40:43], v[180:183], v[104:107], v[40:43]
	ds_read_b128 v[180:183], v9 offset:17024
	s_waitcnt lgkmcnt(9)
	v_mfma_f32_16x16x32_bf16 v[44:47], v[184:187], v[104:107], v[44:47]
	ds_read_b128 v[184:187], v9 offset:25472
	s_waitcnt lgkmcnt(9)
	v_mfma_f32_16x16x32_bf16 v[48:51], v[196:199], v[104:107], v[48:51]
	ds_read_b128 v[196:199], v9 offset:33920
	s_waitcnt lgkmcnt(9)
	v_mfma_f32_16x16x32_bf16 v[32:35], v[200:203], v[108:111], v[32:35]
	ds_read_b128 v[200:203], v9 offset:192
	s_waitcnt lgkmcnt(9)
	v_mfma_f32_16x16x32_bf16 v[36:39], v[204:207], v[108:111], v[36:39]
	ds_read_b128 v[204:207], v9 offset:8640
	s_waitcnt lgkmcnt(9)
	v_mfma_f32_16x16x32_bf16 v[40:43], v[208:211], v[108:111], v[40:43]
	ds_read_b128 v[208:211], v9 offset:17088
	s_waitcnt lgkmcnt(9)
	v_mfma_f32_16x16x32_bf16 v[44:47], v[212:215], v[108:111], v[44:47]
	ds_read_b128 v[212:215], v9 offset:25536
	s_waitcnt lgkmcnt(9)
	v_mfma_f32_16x16x32_bf16 v[48:51], v[234:237], v[108:111], v[48:51]
	ds_read_b128 v[234:237], v9 offset:33984
	s_waitcnt lgkmcnt(9)
	v_mfma_f32_16x16x32_bf16 v[32:35], v[172:175], v[112:115], v[32:35]
	ds_read_b128 v[172:175], v9 offset:256
	s_waitcnt lgkmcnt(9)
	v_mfma_f32_16x16x32_bf16 v[36:39], v[176:179], v[112:115], v[36:39]
	ds_read_b128 v[176:179], v9 offset:8704
	s_waitcnt lgkmcnt(9)
	v_mfma_f32_16x16x32_bf16 v[40:43], v[180:183], v[112:115], v[40:43]
	ds_read_b128 v[180:183], v9 offset:17152
	s_waitcnt lgkmcnt(9)
	v_mfma_f32_16x16x32_bf16 v[44:47], v[184:187], v[112:115], v[44:47]
	ds_read_b128 v[184:187], v9 offset:25600
	s_waitcnt lgkmcnt(9)
	v_mfma_f32_16x16x32_bf16 v[48:51], v[196:199], v[112:115], v[48:51]
	ds_read_b128 v[196:199], v9 offset:34048
	s_waitcnt lgkmcnt(9)
	v_mfma_f32_16x16x32_bf16 v[32:35], v[200:203], v[116:119], v[32:35]
	ds_read_b128 v[200:203], v9 offset:320
	s_waitcnt lgkmcnt(9)
	v_mfma_f32_16x16x32_bf16 v[36:39], v[204:207], v[116:119], v[36:39]
	ds_read_b128 v[204:207], v9 offset:8768
	s_waitcnt lgkmcnt(9)
	v_mfma_f32_16x16x32_bf16 v[40:43], v[208:211], v[116:119], v[40:43]
	ds_read_b128 v[208:211], v9 offset:17216
	s_waitcnt lgkmcnt(9)
	v_mfma_f32_16x16x32_bf16 v[44:47], v[212:215], v[116:119], v[44:47]
	ds_read_b128 v[212:215], v9 offset:25664
	s_waitcnt lgkmcnt(9)
	v_mfma_f32_16x16x32_bf16 v[48:51], v[234:237], v[116:119], v[48:51]
	ds_read_b128 v[234:237], v9 offset:34112
	s_waitcnt lgkmcnt(9)
	v_mfma_f32_16x16x32_bf16 v[32:35], v[172:175], v[120:123], v[32:35]
	ds_read_b128 v[172:175], v9 offset:384
	s_waitcnt lgkmcnt(9)
	v_mfma_f32_16x16x32_bf16 v[36:39], v[176:179], v[120:123], v[36:39]
	ds_read_b128 v[176:179], v9 offset:8832
	s_waitcnt lgkmcnt(9)
	v_mfma_f32_16x16x32_bf16 v[40:43], v[180:183], v[120:123], v[40:43]
	ds_read_b128 v[180:183], v9 offset:17280
	s_waitcnt lgkmcnt(9)
	v_mfma_f32_16x16x32_bf16 v[44:47], v[184:187], v[120:123], v[44:47]
	ds_read_b128 v[184:187], v9 offset:25728
	s_waitcnt lgkmcnt(9)
	v_mfma_f32_16x16x32_bf16 v[48:51], v[196:199], v[120:123], v[48:51]
	ds_read_b128 v[196:199], v9 offset:34176
	s_waitcnt lgkmcnt(9)
	v_mfma_f32_16x16x32_bf16 v[32:35], v[200:203], v[124:127], v[32:35]
	ds_read_b128 v[200:203], v9 offset:448
	s_waitcnt lgkmcnt(9)
	v_mfma_f32_16x16x32_bf16 v[36:39], v[204:207], v[124:127], v[36:39]
	ds_read_b128 v[204:207], v9 offset:8896
	s_waitcnt lgkmcnt(9)
	v_mfma_f32_16x16x32_bf16 v[40:43], v[208:211], v[124:127], v[40:43]
	ds_read_b128 v[208:211], v9 offset:17344
	s_waitcnt lgkmcnt(9)
	v_mfma_f32_16x16x32_bf16 v[44:47], v[212:215], v[124:127], v[44:47]
	ds_read_b128 v[212:215], v9 offset:25792
	s_waitcnt lgkmcnt(9)
	v_mfma_f32_16x16x32_bf16 v[48:51], v[234:237], v[124:127], v[48:51]
	ds_read_b128 v[234:237], v9 offset:34240
	s_waitcnt lgkmcnt(9)
	v_mfma_f32_16x16x32_bf16 v[32:35], v[172:175], v[128:131], v[32:35]
	s_waitcnt lgkmcnt(8)
	v_mfma_f32_16x16x32_bf16 v[36:39], v[176:179], v[128:131], v[36:39]
	s_waitcnt lgkmcnt(7)
	v_mfma_f32_16x16x32_bf16 v[40:43], v[180:183], v[128:131], v[40:43]
	s_waitcnt lgkmcnt(6)
	v_mfma_f32_16x16x32_bf16 v[44:47], v[184:187], v[128:131], v[44:47]
	s_waitcnt lgkmcnt(5)
	v_mfma_f32_16x16x32_bf16 v[48:51], v[196:199], v[128:131], v[48:51]
	s_waitcnt lgkmcnt(4)
	v_mfma_f32_16x16x32_bf16 v[32:35], v[200:203], v[132:135], v[32:35]
	s_waitcnt lgkmcnt(3)
	v_mfma_f32_16x16x32_bf16 v[36:39], v[204:207], v[132:135], v[36:39]
	s_waitcnt lgkmcnt(2)
	v_mfma_f32_16x16x32_bf16 v[40:43], v[208:211], v[132:135], v[40:43]
	s_waitcnt lgkmcnt(1)
	v_mfma_f32_16x16x32_bf16 v[44:47], v[212:215], v[132:135], v[44:47]
	s_waitcnt lgkmcnt(0)
	v_mfma_f32_16x16x32_bf16 v[48:51], v[234:237], v[132:135], v[48:51]
	s_waitcnt vmcnt(8)
	ds_write_b128 v6, v[136:139]
	ds_write_b128 v6, v[140:143] offset:8448
	ds_write_b128 v6, v[144:147] offset:16896
	ds_write_b128 v6, v[148:151] offset:25344
	ds_write_b128 v6, v[152:155] offset:33792
	s_waitcnt lgkmcnt(0)
	s_barrier
	global_load_dwordx4 v[136:139], v5, s[18:19] offset:3584
	global_load_dwordx4 v[140:143], v5, s[28:29] offset:3584
	global_load_dwordx4 v[144:147], v5, s[30:31] offset:3584
	global_load_dwordx4 v[148:151], v5, s[34:35] offset:3584
	global_load_dwordx4 v[152:155], v5, s[36:37] offset:3584
	global_load_dwordx4 v[104:107], v1, s[8:9] offset:3584
	global_load_dwordx4 v[108:111], v1, s[8:9] offset:3648
	global_load_dwordx4 v[112:115], v1, s[8:9] offset:3712
	global_load_dwordx4 v[116:119], v1, s[8:9] offset:3776
	global_load_dwordx4 v[120:123], v1, s[8:9] offset:3840
	global_load_dwordx4 v[124:127], v1, s[8:9] offset:3904
	global_load_dwordx4 v[128:131], v1, s[8:9] offset:3968
	global_load_dwordx4 v[132:135], v1, s[8:9] offset:4032
	s_waitcnt vmcnt(13)
	ds_read_b128 v[172:175], v8
	ds_read_b128 v[176:179], v8 offset:8448
	ds_read_b128 v[180:183], v8 offset:16896
	ds_read_b128 v[184:187], v8 offset:25344
	ds_read_b128 v[196:199], v8 offset:33792
	ds_read_b128 v[200:203], v8 offset:64
	ds_read_b128 v[204:207], v8 offset:8512
	ds_read_b128 v[208:211], v8 offset:16960
	ds_read_b128 v[212:215], v8 offset:25408
	ds_read_b128 v[234:237], v8 offset:33856
	s_waitcnt lgkmcnt(9)
	v_mfma_f32_16x16x32_bf16 v[32:35], v[172:175], v[72:75], v[32:35]
	ds_read_b128 v[172:175], v8 offset:128
	s_waitcnt lgkmcnt(9)
	v_mfma_f32_16x16x32_bf16 v[36:39], v[176:179], v[72:75], v[36:39]
	ds_read_b128 v[176:179], v8 offset:8576
	s_waitcnt lgkmcnt(9)
	v_mfma_f32_16x16x32_bf16 v[40:43], v[180:183], v[72:75], v[40:43]
	ds_read_b128 v[180:183], v8 offset:17024
	s_waitcnt lgkmcnt(9)
	v_mfma_f32_16x16x32_bf16 v[44:47], v[184:187], v[72:75], v[44:47]
	ds_read_b128 v[184:187], v8 offset:25472
	s_waitcnt lgkmcnt(9)
	v_mfma_f32_16x16x32_bf16 v[48:51], v[196:199], v[72:75], v[48:51]
	ds_read_b128 v[196:199], v8 offset:33920
	s_waitcnt lgkmcnt(9)
	v_mfma_f32_16x16x32_bf16 v[32:35], v[200:203], v[76:79], v[32:35]
	ds_read_b128 v[200:203], v8 offset:192
	s_waitcnt lgkmcnt(9)
	v_mfma_f32_16x16x32_bf16 v[36:39], v[204:207], v[76:79], v[36:39]
	ds_read_b128 v[204:207], v8 offset:8640
	s_waitcnt lgkmcnt(9)
	v_mfma_f32_16x16x32_bf16 v[40:43], v[208:211], v[76:79], v[40:43]
	ds_read_b128 v[208:211], v8 offset:17088
	s_waitcnt lgkmcnt(9)
	v_mfma_f32_16x16x32_bf16 v[44:47], v[212:215], v[76:79], v[44:47]
	ds_read_b128 v[212:215], v8 offset:25536
	s_waitcnt lgkmcnt(9)
	v_mfma_f32_16x16x32_bf16 v[48:51], v[234:237], v[76:79], v[48:51]
	ds_read_b128 v[234:237], v8 offset:33984
	s_waitcnt lgkmcnt(9)
	v_mfma_f32_16x16x32_bf16 v[32:35], v[172:175], v[80:83], v[32:35]
	ds_read_b128 v[172:175], v8 offset:256
	s_waitcnt lgkmcnt(9)
	v_mfma_f32_16x16x32_bf16 v[36:39], v[176:179], v[80:83], v[36:39]
	ds_read_b128 v[176:179], v8 offset:8704
	s_waitcnt lgkmcnt(9)
	v_mfma_f32_16x16x32_bf16 v[40:43], v[180:183], v[80:83], v[40:43]
	ds_read_b128 v[180:183], v8 offset:17152
	s_waitcnt lgkmcnt(9)
	v_mfma_f32_16x16x32_bf16 v[44:47], v[184:187], v[80:83], v[44:47]
	ds_read_b128 v[184:187], v8 offset:25600
	s_waitcnt lgkmcnt(9)
	v_mfma_f32_16x16x32_bf16 v[48:51], v[196:199], v[80:83], v[48:51]
	ds_read_b128 v[196:199], v8 offset:34048
	s_waitcnt lgkmcnt(9)
	v_mfma_f32_16x16x32_bf16 v[32:35], v[200:203], v[84:87], v[32:35]
	ds_read_b128 v[200:203], v8 offset:320
	s_waitcnt lgkmcnt(9)
	v_mfma_f32_16x16x32_bf16 v[36:39], v[204:207], v[84:87], v[36:39]
	ds_read_b128 v[204:207], v8 offset:8768
	s_waitcnt lgkmcnt(9)
	v_mfma_f32_16x16x32_bf16 v[40:43], v[208:211], v[84:87], v[40:43]
	ds_read_b128 v[208:211], v8 offset:17216
	s_waitcnt lgkmcnt(9)
	v_mfma_f32_16x16x32_bf16 v[44:47], v[212:215], v[84:87], v[44:47]
	ds_read_b128 v[212:215], v8 offset:25664
	s_waitcnt lgkmcnt(9)
	v_mfma_f32_16x16x32_bf16 v[48:51], v[234:237], v[84:87], v[48:51]
	ds_read_b128 v[234:237], v8 offset:34112
	s_waitcnt lgkmcnt(9)
	v_mfma_f32_16x16x32_bf16 v[32:35], v[172:175], v[88:91], v[32:35]
	ds_read_b128 v[172:175], v8 offset:384
	s_waitcnt lgkmcnt(9)
	v_mfma_f32_16x16x32_bf16 v[36:39], v[176:179], v[88:91], v[36:39]
	ds_read_b128 v[176:179], v8 offset:8832
	s_waitcnt lgkmcnt(9)
	v_mfma_f32_16x16x32_bf16 v[40:43], v[180:183], v[88:91], v[40:43]
	ds_read_b128 v[180:183], v8 offset:17280
	s_waitcnt lgkmcnt(9)
	v_mfma_f32_16x16x32_bf16 v[44:47], v[184:187], v[88:91], v[44:47]
	ds_read_b128 v[184:187], v8 offset:25728
	s_waitcnt lgkmcnt(9)
	v_mfma_f32_16x16x32_bf16 v[48:51], v[196:199], v[88:91], v[48:51]
	ds_read_b128 v[196:199], v8 offset:34176
	s_waitcnt lgkmcnt(9)
	v_mfma_f32_16x16x32_bf16 v[32:35], v[200:203], v[92:95], v[32:35]
	ds_read_b128 v[200:203], v8 offset:448
	s_waitcnt lgkmcnt(9)
	v_mfma_f32_16x16x32_bf16 v[36:39], v[204:207], v[92:95], v[36:39]
	ds_read_b128 v[204:207], v8 offset:8896
	s_waitcnt lgkmcnt(9)
	v_mfma_f32_16x16x32_bf16 v[40:43], v[208:211], v[92:95], v[40:43]
	ds_read_b128 v[208:211], v8 offset:17344
	s_waitcnt lgkmcnt(9)
	v_mfma_f32_16x16x32_bf16 v[44:47], v[212:215], v[92:95], v[44:47]
	ds_read_b128 v[212:215], v8 offset:25792
	s_waitcnt lgkmcnt(9)
	v_mfma_f32_16x16x32_bf16 v[48:51], v[234:237], v[92:95], v[48:51]
	ds_read_b128 v[234:237], v8 offset:34240
	s_waitcnt lgkmcnt(9)
	v_mfma_f32_16x16x32_bf16 v[32:35], v[172:175], v[96:99], v[32:35]
	s_waitcnt lgkmcnt(8)
	v_mfma_f32_16x16x32_bf16 v[36:39], v[176:179], v[96:99], v[36:39]
	s_waitcnt lgkmcnt(7)
	v_mfma_f32_16x16x32_bf16 v[40:43], v[180:183], v[96:99], v[40:43]
	s_waitcnt lgkmcnt(6)
	v_mfma_f32_16x16x32_bf16 v[44:47], v[184:187], v[96:99], v[44:47]
	s_waitcnt lgkmcnt(5)
	v_mfma_f32_16x16x32_bf16 v[48:51], v[196:199], v[96:99], v[48:51]
	s_waitcnt lgkmcnt(4)
	v_mfma_f32_16x16x32_bf16 v[32:35], v[200:203], v[100:103], v[32:35]
	s_waitcnt lgkmcnt(3)
	v_mfma_f32_16x16x32_bf16 v[36:39], v[204:207], v[100:103], v[36:39]
	s_waitcnt lgkmcnt(2)
	v_mfma_f32_16x16x32_bf16 v[40:43], v[208:211], v[100:103], v[40:43]
	s_waitcnt lgkmcnt(1)
	v_mfma_f32_16x16x32_bf16 v[44:47], v[212:215], v[100:103], v[44:47]
	s_waitcnt lgkmcnt(0)
	v_mfma_f32_16x16x32_bf16 v[48:51], v[234:237], v[100:103], v[48:51]
	s_waitcnt vmcnt(8)
	ds_write_b128 v7, v[136:139]
	ds_write_b128 v7, v[140:143] offset:8448
	ds_write_b128 v7, v[144:147] offset:16896
	ds_write_b128 v7, v[148:151] offset:25344
	ds_write_b128 v7, v[152:155] offset:33792
	s_waitcnt lgkmcnt(0)
	s_barrier
	s_waitcnt vmcnt(0)
	ds_read_b128 v[172:175], v9
	ds_read_b128 v[176:179], v9 offset:8448
	ds_read_b128 v[180:183], v9 offset:16896
	ds_read_b128 v[184:187], v9 offset:25344
	ds_read_b128 v[196:199], v9 offset:33792
	ds_read_b128 v[200:203], v9 offset:64
	ds_read_b128 v[204:207], v9 offset:8512
	ds_read_b128 v[208:211], v9 offset:16960
	ds_read_b128 v[212:215], v9 offset:25408
	ds_read_b128 v[234:237], v9 offset:33856
	s_waitcnt lgkmcnt(9)
	v_mfma_f32_16x16x32_bf16 v[32:35], v[172:175], v[104:107], v[32:35]
	ds_read_b128 v[172:175], v9 offset:128
	s_waitcnt lgkmcnt(9)
	v_mfma_f32_16x16x32_bf16 v[36:39], v[176:179], v[104:107], v[36:39]
	ds_read_b128 v[176:179], v9 offset:8576
	s_waitcnt lgkmcnt(9)
	v_mfma_f32_16x16x32_bf16 v[40:43], v[180:183], v[104:107], v[40:43]
	ds_read_b128 v[180:183], v9 offset:17024
	s_waitcnt lgkmcnt(9)
	v_mfma_f32_16x16x32_bf16 v[44:47], v[184:187], v[104:107], v[44:47]
	ds_read_b128 v[184:187], v9 offset:25472
	s_waitcnt lgkmcnt(9)
	v_mfma_f32_16x16x32_bf16 v[48:51], v[196:199], v[104:107], v[48:51]
	ds_read_b128 v[196:199], v9 offset:33920
	s_waitcnt lgkmcnt(9)
	v_mfma_f32_16x16x32_bf16 v[32:35], v[200:203], v[108:111], v[32:35]
	ds_read_b128 v[200:203], v9 offset:192
	s_waitcnt lgkmcnt(9)
	v_mfma_f32_16x16x32_bf16 v[36:39], v[204:207], v[108:111], v[36:39]
	ds_read_b128 v[204:207], v9 offset:8640
	s_waitcnt lgkmcnt(9)
	v_mfma_f32_16x16x32_bf16 v[40:43], v[208:211], v[108:111], v[40:43]
	ds_read_b128 v[208:211], v9 offset:17088
	s_waitcnt lgkmcnt(9)
	v_mfma_f32_16x16x32_bf16 v[44:47], v[212:215], v[108:111], v[44:47]
	ds_read_b128 v[212:215], v9 offset:25536
	s_waitcnt lgkmcnt(9)
	v_mfma_f32_16x16x32_bf16 v[48:51], v[234:237], v[108:111], v[48:51]
	ds_read_b128 v[234:237], v9 offset:33984
	s_waitcnt lgkmcnt(9)
	v_mfma_f32_16x16x32_bf16 v[32:35], v[172:175], v[112:115], v[32:35]
	ds_read_b128 v[172:175], v9 offset:256
	s_waitcnt lgkmcnt(9)
	v_mfma_f32_16x16x32_bf16 v[36:39], v[176:179], v[112:115], v[36:39]
	ds_read_b128 v[176:179], v9 offset:8704
	s_waitcnt lgkmcnt(9)
	v_mfma_f32_16x16x32_bf16 v[40:43], v[180:183], v[112:115], v[40:43]
	ds_read_b128 v[180:183], v9 offset:17152
	s_waitcnt lgkmcnt(9)
	v_mfma_f32_16x16x32_bf16 v[44:47], v[184:187], v[112:115], v[44:47]
	ds_read_b128 v[184:187], v9 offset:25600
	s_waitcnt lgkmcnt(9)
	v_mfma_f32_16x16x32_bf16 v[48:51], v[196:199], v[112:115], v[48:51]
	ds_read_b128 v[196:199], v9 offset:34048
	s_waitcnt lgkmcnt(9)
	v_mfma_f32_16x16x32_bf16 v[32:35], v[200:203], v[116:119], v[32:35]
	ds_read_b128 v[200:203], v9 offset:320
	s_waitcnt lgkmcnt(9)
	v_mfma_f32_16x16x32_bf16 v[36:39], v[204:207], v[116:119], v[36:39]
	ds_read_b128 v[204:207], v9 offset:8768
	s_waitcnt lgkmcnt(9)
	v_mfma_f32_16x16x32_bf16 v[40:43], v[208:211], v[116:119], v[40:43]
	ds_read_b128 v[208:211], v9 offset:17216
	s_waitcnt lgkmcnt(9)
	v_mfma_f32_16x16x32_bf16 v[44:47], v[212:215], v[116:119], v[44:47]
	ds_read_b128 v[212:215], v9 offset:25664
	s_waitcnt lgkmcnt(9)
	v_mfma_f32_16x16x32_bf16 v[48:51], v[234:237], v[116:119], v[48:51]
	ds_read_b128 v[234:237], v9 offset:34112
	s_waitcnt lgkmcnt(9)
	v_mfma_f32_16x16x32_bf16 v[32:35], v[172:175], v[120:123], v[32:35]
	ds_read_b128 v[172:175], v9 offset:384
	s_waitcnt lgkmcnt(9)
	v_mfma_f32_16x16x32_bf16 v[36:39], v[176:179], v[120:123], v[36:39]
	ds_read_b128 v[176:179], v9 offset:8832
	s_waitcnt lgkmcnt(9)
	v_mfma_f32_16x16x32_bf16 v[40:43], v[180:183], v[120:123], v[40:43]
	ds_read_b128 v[180:183], v9 offset:17280
	s_waitcnt lgkmcnt(9)
	v_mfma_f32_16x16x32_bf16 v[44:47], v[184:187], v[120:123], v[44:47]
	ds_read_b128 v[184:187], v9 offset:25728
	s_waitcnt lgkmcnt(9)
	v_mfma_f32_16x16x32_bf16 v[48:51], v[196:199], v[120:123], v[48:51]
	ds_read_b128 v[196:199], v9 offset:34176
	s_waitcnt lgkmcnt(9)
	v_mfma_f32_16x16x32_bf16 v[32:35], v[200:203], v[124:127], v[32:35]
	ds_read_b128 v[200:203], v9 offset:448
	s_waitcnt lgkmcnt(9)
	v_mfma_f32_16x16x32_bf16 v[36:39], v[204:207], v[124:127], v[36:39]
	ds_read_b128 v[204:207], v9 offset:8896
	s_waitcnt lgkmcnt(9)
	v_mfma_f32_16x16x32_bf16 v[40:43], v[208:211], v[124:127], v[40:43]
	ds_read_b128 v[208:211], v9 offset:17344
	s_waitcnt lgkmcnt(9)
	v_mfma_f32_16x16x32_bf16 v[44:47], v[212:215], v[124:127], v[44:47]
	ds_read_b128 v[212:215], v9 offset:25792
	s_waitcnt lgkmcnt(9)
	v_mfma_f32_16x16x32_bf16 v[48:51], v[234:237], v[124:127], v[48:51]
	ds_read_b128 v[234:237], v9 offset:34240
	s_waitcnt lgkmcnt(9)
	v_mfma_f32_16x16x32_bf16 v[32:35], v[172:175], v[128:131], v[32:35]
	s_waitcnt lgkmcnt(8)
	v_mfma_f32_16x16x32_bf16 v[36:39], v[176:179], v[128:131], v[36:39]
	s_waitcnt lgkmcnt(7)
	v_mfma_f32_16x16x32_bf16 v[40:43], v[180:183], v[128:131], v[40:43]
	s_waitcnt lgkmcnt(6)
	v_mfma_f32_16x16x32_bf16 v[44:47], v[184:187], v[128:131], v[44:47]
	s_waitcnt lgkmcnt(5)
	v_mfma_f32_16x16x32_bf16 v[48:51], v[196:199], v[128:131], v[48:51]
	s_waitcnt lgkmcnt(4)
	v_mfma_f32_16x16x32_bf16 v[32:35], v[200:203], v[132:135], v[32:35]
	s_waitcnt lgkmcnt(3)
	v_mfma_f32_16x16x32_bf16 v[36:39], v[204:207], v[132:135], v[36:39]
	s_waitcnt lgkmcnt(2)
	v_mfma_f32_16x16x32_bf16 v[40:43], v[208:211], v[132:135], v[40:43]
	s_waitcnt lgkmcnt(1)
	v_mfma_f32_16x16x32_bf16 v[44:47], v[212:215], v[132:135], v[44:47]
	s_waitcnt lgkmcnt(0)
	v_mfma_f32_16x16x32_bf16 v[48:51], v[234:237], v[132:135], v[48:51]
	global_load_dwordx4 v[72:75], v3, s[38:39]
	global_load_dwordx4 v[76:79], v3, s[38:39] offset:64
	global_load_dwordx4 v[80:83], v3, s[38:39] offset:128
	global_load_dwordx4 v[84:87], v3, s[38:39] offset:192
	global_load_dwordx4 v[88:91], v3, s[38:39] offset:256
	s_nop 7
	s_waitcnt vmcnt(0)
	v_add_f32_e32 v32, v32, v72
	v_add_f32_e32 v33, v33, v73
	v_add_f32_e32 v34, v34, v74
	v_add_f32_e32 v35, v35, v75
	v_add_f32_e32 v36, v36, v76
	v_add_f32_e32 v37, v37, v77
	v_add_f32_e32 v38, v38, v78
	v_add_f32_e32 v39, v39, v79
	v_add_f32_e32 v40, v40, v80
	v_add_f32_e32 v41, v41, v81
	v_add_f32_e32 v42, v42, v82
	v_add_f32_e32 v43, v43, v83
	v_add_f32_e32 v44, v44, v84
	v_add_f32_e32 v45, v45, v85
	v_add_f32_e32 v46, v46, v86
	v_add_f32_e32 v47, v47, v87
	v_add_f32_e32 v48, v48, v88
	v_add_f32_e32 v49, v49, v89
	v_add_f32_e32 v50, v50, v90
	v_add_f32_e32 v51, v51, v91
	s_nop 1
	global_store_dwordx4 v2, v[32:35], s[40:41]
	global_store_dwordx4 v2, v[36:39], s[40:41] offset:64
	global_store_dwordx4 v2, v[40:43], s[40:41] offset:128
	global_store_dwordx4 v2, v[44:47], s[40:41] offset:192
	global_store_dwordx4 v2, v[48:51], s[40:41] offset:256
	s_nop 1
	s_add_i32 s48, s48, s49
	s_cmpk_gt_u32 s48, 0x87
	s_cbranch_scc0 .Lmisc_pass
